# mLSTM conv weights/bias staged in LDS once per item, read via ds_read_b128 in interval A instead of 10 global loads per chunk
# baseline (speedup 1.0000x reference)
.LBB0_181:
	s_or_b64 exec, exec, s[44:45]
	s_lshl_b32 s50, s4, 7
	s_add_i32 s51, s50, 0x180
	v_and_b32_e32 v8, 31, v222
	v_lshlrev_b32_e32 v9, 3, v8
	v_add_u32_e32 v10, s51, v9
	v_or_b32_e32 v9, s50, v9
	v_cmp_lt_u32_e32 vcc, 15, v8
	v_lshrrev_b32_e32 v12, 5, v222
	v_and_b32_e32 v11, 1, v12
	v_cndmask_b32_e32 v9, v9, v10, vcc
	v_lshl_add_u32 v9, v11, 2, v9
	v_lshrrev_b32_e32 v11, 1, v12
	v_lshl_add_u32 v11, v11, 10, v9
	v_lshlrev_b32_e32 v11, 2, v11
	v_lshlrev_b32_e32 v9, 2, v9
	v_cmp_gt_u32_e32 vcc, 8, v12
	s_and_saveexec_b64 s[46:47], vcc
	global_load_dwordx4 v[16:19], v11, s[64:65]
	s_mov_b64 exec, s[46:47]
	v_and_b32_e32 v13, 14, v12
	v_cmp_eq_u32_e32 vcc, 8, v13
	s_and_saveexec_b64 s[46:47], vcc
	global_load_dwordx4 v[16:19], v9, s[66:67]
	s_mov_b64 exec, s[46:47]
	v_lshlrev_b32_e32 v13, 4, v222
	v_add_u32_e32 v13, 0x21a00, v13
	v_cmp_gt_u32_e32 vcc, 0x140, v222
	s_waitcnt vmcnt(0)
	s_and_saveexec_b64 s[46:47], vcc
	ds_write_b128 v13, v[16:19]
	s_mov_b64 exec, s[46:47]
	v_cmp_gt_i32_e32 vcc, 64, v5
	s_waitcnt lgkmcnt(0)
	s_barrier
	s_and_saveexec_b64 s[44:45], vcc
	s_cbranch_execz .LBB0_186
	s_mov_b32 s3, 0
	v_mov_b32_e32 v2, 0
	v_mov_b32_e32 v0, 0
	v_mov_b32_e32 v1, 0

.LBB0_211:
	v_and_b32_e32 v215, 31, v214
	v_lshlrev_b32_e32 v64, 3, v215
	v_add_u32_e32 v65, s33, v64
	v_or_b32_e32 v64, s55, v64
	v_cmp_lt_u32_e64 s[44:45], 15, v215
	s_movk_i32 s12, 0x2000
	s_waitcnt vmcnt(0)
	v_lshlrev_b32_e32 v166, 16, v104
	v_cndmask_b32_e64 v169, v64, v65, s[44:45]
	v_lshlrev_b32_e32 v96, 2, v169
	v_lshlrev_b32_e32 v171, 4, v215
	v_add_u32_e32 v171, 0x21a00, v171
	v_and_b32_e32 v167, 0xffff0000, v104
	s_mov_b64 s[12:13], 0x3000
	ds_read_b128 v[84:87], v171 offset:1024
	ds_read_b128 v[88:91], v171
	ds_read_b128 v[92:95], v171 offset:4096
	ds_read_b128 v[156:159], v171 offset:2048
	ds_read_b128 v[160:163], v171 offset:3072
	ds_read_b128 v[64:67], v171 offset:512
	ds_read_b128 v[68:71], v171 offset:4608
	ds_read_b128 v[72:75], v171 offset:1536
	ds_read_b128 v[76:79], v171 offset:2560
	ds_read_b128 v[80:83], v171 offset:3584
	v_lshlrev_b32_e32 v172, 16, v100
	v_and_b32_e32 v173, 0xffff0000, v100
	v_lshlrev_b32_e32 v174, 16, v108
	v_and_b32_e32 v175, 0xffff0000, v108
	v_lshlrev_b32_e32 v176, 16, v112
	v_and_b32_e32 v177, 0xffff0000, v112
	v_lshlrev_b32_e32 v178, 16, v116
	v_and_b32_e32 v179, 0xffff0000, v116
	v_lshlrev_b32_e32 v180, 16, v120
	v_and_b32_e32 v181, 0xffff0000, v120
	v_lshlrev_b32_e32 v182, 16, v124
	v_and_b32_e32 v183, 0xffff0000, v124
	v_ashrrev_i32_e32 v170, 5, v214
	s_movk_i32 s12, 0x440
	v_cmp_gt_u32_e32 vcc, 16, v215
	s_waitcnt lgkmcnt(7)
	v_pk_fma_f32 v[166:167], v[88:89], v[166:167], v[92:93]
	v_pk_fma_f32 v[184:185], v[88:89], v[172:173], v[92:93]
	v_pk_fma_f32 v[186:187], v[88:89], v[174:175], v[92:93]
	v_pk_fma_f32 v[88:89], v[88:89], v[176:177], v[92:93]
	v_pk_fma_f32 v[92:93], v[84:85], v[172:173], v[166:167]
	v_pk_fma_f32 v[166:167], v[84:85], v[174:175], v[184:185]
	v_pk_fma_f32 v[172:173], v[84:85], v[176:177], v[186:187]
	v_pk_fma_f32 v[84:85], v[84:85], v[178:179], v[88:89]
	s_waitcnt lgkmcnt(6)
	v_pk_fma_f32 v[88:89], v[156:157], v[174:175], v[92:93]
	v_pk_fma_f32 v[92:93], v[156:157], v[176:177], v[166:167]
	v_pk_fma_f32 v[166:167], v[156:157], v[178:179], v[172:173]
	v_pk_fma_f32 v[84:85], v[156:157], v[180:181], v[84:85]
	s_waitcnt lgkmcnt(5)
	v_pk_fma_f32 v[88:89], v[160:161], v[176:177], v[88:89]
	v_pk_fma_f32 v[156:157], v[160:161], v[178:179], v[92:93]
	v_pk_fma_f32 v[166:167], v[160:161], v[180:181], v[166:167]
	v_pk_fma_f32 v[160:161], v[160:161], v[182:183], v[84:85]
	v_mul_f32_e32 v84, 0xbfb8aa3b, v88
	v_mul_f32_e32 v85, 0xbfb8aa3b, v89
	v_mul_f32_e32 v92, 0xbfb8aa3b, v156
	v_mul_f32_e32 v93, 0xbfb8aa3b, v157
	v_mul_f32_e32 v96, 0xbfb8aa3b, v166
	v_mul_f32_e32 v171, 0xbfb8aa3b, v167
	v_mul_f32_e32 v172, 0xbfb8aa3b, v160
	v_mul_f32_e32 v173, 0xbfb8aa3b, v161
	v_exp_f32_e32 v84, v84
	v_exp_f32_e32 v85, v85
	v_exp_f32_e32 v92, v92
	v_exp_f32_e32 v93, v93
	v_exp_f32_e32 v96, v96
	v_exp_f32_e32 v171, v171
	v_exp_f32_e32 v172, v172
	v_exp_f32_e32 v173, v173
	v_add_f32_e32 v84, 1.0, v84
	v_add_f32_e32 v85, 1.0, v85
	v_add_f32_e32 v92, 1.0, v92
	v_add_f32_e32 v93, 1.0, v93
	v_add_f32_e32 v96, 1.0, v96
	v_add_f32_e32 v171, 1.0, v171
	v_add_f32_e32 v176, 1.0, v172
	v_add_f32_e32 v177, 1.0, v173
	v_rcp_f32_e32 v84, v84
	v_rcp_f32_e32 v85, v85
	v_rcp_f32_e32 v172, v92
	v_rcp_f32_e32 v173, v93
	v_rcp_f32_e32 v174, v96
	v_rcp_f32_e32 v175, v171
	v_pk_mul_f32 v[92:93], v[88:89], v[84:85]
	v_pk_mul_f32 v[88:89], v[156:157], v[172:173]
	v_lshlrev_b32_e32 v156, 16, v105
	v_and_b32_e32 v157, 0xffff0000, v105
	v_pk_mul_f32 v[84:85], v[166:167], v[174:175]
	v_lshlrev_b32_e32 v166, 16, v101
	v_and_b32_e32 v167, 0xffff0000, v101
	v_pk_fma_f32 v[156:157], v[90:91], v[156:157], v[94:95]
	v_lshlrev_b32_e32 v172, 16, v109
	v_and_b32_e32 v173, 0xffff0000, v109
	v_pk_fma_f32 v[156:157], v[86:87], v[166:167], v[156:157]
	v_lshlrev_b32_e32 v174, 16, v113
	v_and_b32_e32 v175, 0xffff0000, v113
	v_pk_fma_f32 v[156:157], v[158:159], v[172:173], v[156:157]
	v_rcp_f32_e32 v176, v176
	v_pk_fma_f32 v[178:179], v[162:163], v[174:175], v[156:157]
	v_rcp_f32_e32 v177, v177
	v_mul_f32_e32 v96, 0xbfb8aa3b, v178
	v_exp_f32_e32 v96, v96
	v_mul_f32_e32 v156, 0xbfb8aa3b, v179
	v_exp_f32_e32 v171, v156
	v_pk_fma_f32 v[166:167], v[90:91], v[166:167], v[94:95]
	v_pk_mul_f32 v[156:157], v[160:161], v[176:177]
	v_pk_fma_f32 v[166:167], v[86:87], v[172:173], v[166:167]
	v_add_f32_e32 v96, 1.0, v96
	v_lshlrev_b32_e32 v176, 16, v117
	v_and_b32_e32 v177, 0xffff0000, v117
	v_pk_fma_f32 v[166:167], v[158:159], v[174:175], v[166:167]
	v_rcp_f32_e32 v160, v96
	v_add_f32_e32 v96, 1.0, v171
	v_pk_fma_f32 v[166:167], v[162:163], v[176:177], v[166:167]
	v_rcp_f32_e32 v161, v96
	v_mul_f32_e32 v96, 0xbfb8aa3b, v166
	v_exp_f32_e32 v96, v96
	v_mul_f32_e32 v171, 0xbfb8aa3b, v167
	v_exp_f32_e32 v171, v171
	v_pk_fma_f32 v[172:173], v[90:91], v[172:173], v[94:95]
	v_add_f32_e32 v96, 1.0, v96
	v_pk_fma_f32 v[172:173], v[86:87], v[174:175], v[172:173]
	v_lshlrev_b32_e32 v180, 16, v121
	v_and_b32_e32 v181, 0xffff0000, v121
	v_pk_fma_f32 v[172:173], v[158:159], v[176:177], v[172:173]
	v_pk_mul_f32 v[160:161], v[178:179], v[160:161]
	v_rcp_f32_e32 v178, v96
	v_add_f32_e32 v96, 1.0, v171
	v_pk_fma_f32 v[172:173], v[162:163], v[180:181], v[172:173]
	v_rcp_f32_e32 v179, v96
	v_mul_f32_e32 v96, 0xbfb8aa3b, v172
	v_exp_f32_e32 v96, v96
	v_mul_f32_e32 v171, 0xbfb8aa3b, v173
	v_exp_f32_e32 v171, v171
	v_pk_fma_f32 v[90:91], v[90:91], v[174:175], v[94:95]
	v_add_f32_e32 v96, 1.0, v96
	v_pk_fma_f32 v[86:87], v[86:87], v[176:177], v[90:91]
	v_pk_mul_f32 v[166:167], v[166:167], v[178:179]
	v_rcp_f32_e32 v178, v96
	v_add_f32_e32 v96, 1.0, v171
	v_lshlrev_b32_e32 v182, 16, v125
	v_and_b32_e32 v183, 0xffff0000, v125
	v_pk_fma_f32 v[86:87], v[158:159], v[180:181], v[86:87]
	v_rcp_f32_e32 v179, v96
	v_pk_fma_f32 v[90:91], v[162:163], v[182:183], v[86:87]
	v_lshlrev_b32_e32 v158, 16, v106
	v_mul_f32_e32 v86, 0xbfb8aa3b, v90
	v_exp_f32_e32 v94, v86
	v_mul_f32_e32 v86, 0xbfb8aa3b, v91
	v_and_b32_e32 v159, 0xffff0000, v106
	v_exp_f32_e32 v95, v86
	v_lshlrev_b32_e32 v162, 16, v102
	v_and_b32_e32 v163, 0xffff0000, v102
	s_waitcnt lgkmcnt(3)
	v_pk_fma_f32 v[158:159], v[64:65], v[158:159], v[68:69]
	v_pk_mul_f32 v[86:87], v[172:173], v[178:179]
	v_lshlrev_b32_e32 v172, 16, v110
	v_and_b32_e32 v173, 0xffff0000, v110
	s_waitcnt lgkmcnt(2)
	v_pk_fma_f32 v[158:159], v[72:73], v[162:163], v[158:159]
	v_lshlrev_b32_e32 v174, 16, v114
	v_and_b32_e32 v175, 0xffff0000, v114
	s_waitcnt lgkmcnt(1)
	v_pk_fma_f32 v[158:159], v[76:77], v[172:173], v[158:159]
	v_add_f32_e32 v94, 1.0, v94
	s_waitcnt lgkmcnt(0)
	v_pk_fma_f32 v[158:159], v[80:81], v[174:175], v[158:159]
	v_add_f32_e32 v95, 1.0, v95
	v_mul_f32_e32 v96, 0xbfb8aa3b, v158
	v_rcp_f32_e32 v94, v94
	v_rcp_f32_e32 v95, v95
	v_exp_f32_e32 v96, v96
	v_mul_f32_e32 v171, 0xbfb8aa3b, v159
	v_pk_fma_f32 v[162:163], v[64:65], v[162:163], v[68:69]
	v_exp_f32_e32 v171, v171
	v_pk_fma_f32 v[162:163], v[72:73], v[172:173], v[162:163]
	v_lshlrev_b32_e32 v176, 16, v118
	v_and_b32_e32 v177, 0xffff0000, v118
	v_pk_fma_f32 v[162:163], v[76:77], v[174:175], v[162:163]
	v_pk_mul_f32 v[90:91], v[90:91], v[94:95]
	v_pk_fma_f32 v[162:163], v[80:81], v[176:177], v[162:163]
	v_add_f32_e32 v94, 1.0, v96
	v_mul_f32_e32 v96, 0xbfb8aa3b, v162
	v_add_f32_e32 v95, 1.0, v171
	v_exp_f32_e32 v96, v96
	v_mul_f32_e32 v171, 0xbfb8aa3b, v163
	v_rcp_f32_e32 v94, v94
	v_rcp_f32_e32 v95, v95
	v_exp_f32_e32 v171, v171
	v_pk_fma_f32 v[172:173], v[64:65], v[172:173], v[68:69]
	v_add_f32_e32 v96, 1.0, v96
	v_pk_fma_f32 v[172:173], v[72:73], v[174:175], v[172:173]
	v_lshlrev_b32_e32 v178, 16, v122
	v_and_b32_e32 v179, 0xffff0000, v122
	v_pk_fma_f32 v[172:173], v[76:77], v[176:177], v[172:173]
	v_pk_mul_f32 v[94:95], v[158:159], v[94:95]
	v_rcp_f32_e32 v158, v96
	v_add_f32_e32 v96, 1.0, v171
	v_pk_fma_f32 v[172:173], v[80:81], v[178:179], v[172:173]
	v_rcp_f32_e32 v159, v96
	v_mul_f32_e32 v96, 0xbfb8aa3b, v172
	v_exp_f32_e32 v96, v96
	v_mul_f32_e32 v171, 0xbfb8aa3b, v173
	v_exp_f32_e32 v171, v171
	v_pk_fma_f32 v[64:65], v[64:65], v[174:175], v[68:69]
	v_add_f32_e32 v96, 1.0, v96
	v_pk_fma_f32 v[64:65], v[72:73], v[176:177], v[64:65]
	v_lshlrev_b32_e32 v180, 16, v126
	v_and_b32_e32 v181, 0xffff0000, v126
	v_pk_fma_f32 v[64:65], v[76:77], v[178:179], v[64:65]
	v_pk_mul_f32 v[158:159], v[162:163], v[158:159]
	v_rcp_f32_e32 v162, v96
	v_add_f32_e32 v96, 1.0, v171
	v_pk_fma_f32 v[64:65], v[80:81], v[180:181], v[64:65]
	v_rcp_f32_e32 v163, v96
	v_mul_f32_e32 v68, 0xbfb8aa3b, v64
	v_mul_f32_e32 v69, 0xbfb8aa3b, v65
	v_exp_f32_e32 v68, v68
	v_exp_f32_e32 v69, v69
	v_lshlrev_b32_e32 v72, 16, v107
	v_and_b32_e32 v73, 0xffff0000, v107
	v_lshlrev_b32_e32 v80, 16, v103
	v_and_b32_e32 v81, 0xffff0000, v103
	v_pk_fma_f32 v[72:73], v[66:67], v[72:73], v[70:71]
	v_pk_mul_f32 v[76:77], v[172:173], v[162:163]
	v_lshlrev_b32_e32 v162, 16, v111
	v_and_b32_e32 v163, 0xffff0000, v111
	v_pk_fma_f32 v[72:73], v[74:75], v[80:81], v[72:73]
	v_add_f32_e32 v68, 1.0, v68
	v_add_f32_e32 v69, 1.0, v69
	v_lshlrev_b32_e32 v172, 16, v115
	v_and_b32_e32 v173, 0xffff0000, v115
	v_pk_fma_f32 v[72:73], v[78:79], v[162:163], v[72:73]
	v_rcp_f32_e32 v68, v68
	v_rcp_f32_e32 v69, v69
	v_pk_fma_f32 v[174:175], v[82:83], v[172:173], v[72:73]
	v_pk_fma_f32 v[80:81], v[66:67], v[80:81], v[70:71]
	v_mul_f32_e32 v72, 0xbfb8aa3b, v174
	v_exp_f32_e32 v96, v72
	v_mul_f32_e32 v72, 0xbfb8aa3b, v175
	v_exp_f32_e32 v171, v72
	v_pk_fma_f32 v[80:81], v[74:75], v[162:163], v[80:81]
	v_pk_mul_f32 v[72:73], v[64:65], v[68:69]
	v_lshlrev_b32_e32 v68, 16, v119
	v_and_b32_e32 v69, 0xffff0000, v119
	v_pk_fma_f32 v[80:81], v[78:79], v[172:173], v[80:81]
	v_add_f32_e32 v64, 1.0, v96
	v_pk_fma_f32 v[80:81], v[82:83], v[68:69], v[80:81]
	v_add_f32_e32 v65, 1.0, v171
	v_mul_f32_e32 v96, 0xbfb8aa3b, v80
	v_exp_f32_e32 v96, v96
	v_mul_f32_e32 v171, 0xbfb8aa3b, v81
	v_pk_fma_f32 v[162:163], v[66:67], v[162:163], v[70:71]
	v_pk_fma_f32 v[66:67], v[66:67], v[172:173], v[70:71]
	v_exp_f32_e32 v171, v171
	v_lshlrev_b32_e32 v178, 16, v123
	v_and_b32_e32 v179, 0xffff0000, v123
	v_pk_fma_f32 v[66:67], v[74:75], v[68:69], v[66:67]
	v_pk_fma_f32 v[162:163], v[74:75], v[172:173], v[162:163]
	v_lshlrev_b32_e32 v182, 16, v127
	v_and_b32_e32 v183, 0xffff0000, v127
	v_pk_fma_f32 v[66:67], v[78:79], v[178:179], v[66:67]
	v_pk_fma_f32 v[162:163], v[78:79], v[68:69], v[162:163]
	v_pk_fma_f32 v[74:75], v[82:83], v[182:183], v[66:67]
	v_add_f32_e32 v96, 1.0, v96
	v_pk_fma_f32 v[162:163], v[82:83], v[178:179], v[162:163]
	v_mul_f32_e32 v66, 0xbfb8aa3b, v74
	v_rcp_f32_e32 v176, v96
	v_add_f32_e32 v96, 1.0, v171
	v_mul_f32_e32 v171, 0xbfb8aa3b, v162
	v_exp_f32_e32 v66, v66
	v_mul_f32_e32 v67, 0xbfb8aa3b, v75
	v_exp_f32_e32 v171, v171
	v_mul_f32_e32 v177, 0xbfb8aa3b, v163
	v_exp_f32_e32 v67, v67
	v_exp_f32_e32 v181, v177
	v_add_f32_e32 v66, 1.0, v66
	v_rcp_f32_e32 v177, v96
	v_add_f32_e32 v96, 1.0, v171
	v_rcp_f32_e32 v78, v66
	v_add_f32_e32 v66, 1.0, v67
	v_rcp_f32_e32 v64, v64
	v_rcp_f32_e32 v65, v65
	v_rcp_f32_e32 v180, v96
	v_add_f32_e32 v96, 1.0, v181
	v_rcp_f32_e32 v79, v66
	v_rcp_f32_e32 v181, v96
	v_pk_mul_f32 v[70:71], v[174:175], v[64:65]
	v_pk_mul_f32 v[68:69], v[80:81], v[176:177]
	v_pk_mul_f32 v[64:65], v[74:75], v[78:79]
	v_lshlrev_b32_e32 v74, 4, v215
	v_mul_lo_u32 v75, v170, s12
	v_pk_mul_f32 v[66:67], v[162:163], v[180:181]
	v_add3_u32 v96, 0, v74, v75
	s_and_saveexec_b64 s[12:13], vcc
	s_xor_b64 s[12:13], exec, s[12:13]
	s_cbranch_execz .LBB0_213
	v_cvt_pk_bf16_f32 v78, v92, v93
	v_cvt_pk_bf16_f32 v79, v160, v161
	v_cvt_pk_bf16_f32 v80, v94, v95
	v_cvt_pk_bf16_f32 v81, v70, v71
	ds_write_b128 v96, v[78:81]
	v_cvt_pk_bf16_f32 v81, v68, v69
	v_cvt_pk_bf16_f32 v68, v84, v85
	v_cvt_pk_bf16_f32 v69, v86, v87
	v_cvt_pk_bf16_f32 v70, v76, v77
	v_cvt_pk_bf16_f32 v71, v66, v67
	v_cvt_pk_bf16_f32 v78, v88, v89
	v_cvt_pk_bf16_f32 v79, v166, v167
	v_cvt_pk_bf16_f32 v80, v158, v159
	ds_write_b128 v96, v[68:71] offset:544
	v_cvt_pk_bf16_f32 v66, v156, v157
	v_cvt_pk_bf16_f32 v67, v90, v91
	v_cvt_pk_bf16_f32 v68, v72, v73
	v_cvt_pk_bf16_f32 v69, v64, v65
	ds_write_b128 v96, v[78:81] offset:272
	ds_write_b128 v96, v[66:69] offset:816
